# row-tile barriers with the correct tile owner map (pm = 8*(bx&7) + 2*(bx>>6) + ((bx>>3)&1), WGM=2 order): seams 3-4, 5-6, 11-12, 13-14, 16-17 wait only for the four CUs of the same 256-row tile
# speedup vs baseline: 1.0002x; 1.0002x over previous
.LBB0_595:
	s_cmp_eq_u32 s100, 0
	s_cbranch_scc1 .Lbar_slow
	s_lshl_b32 s4, 1, s73
	s_and_b32 s4, s4, 0x12828
	s_cmp_eq_u32 s4, 0
	s_cbranch_scc1 .Lbar_slow
	s_mov_b32 s2, 1
	s_cmp_ge_u32 s73, 5
	s_addc_u32 s2, s2, 0
	s_cmp_ge_u32 s73, 11
	s_addc_u32 s2, s2, 0
	s_cmp_ge_u32 s73, 13
	s_addc_u32 s2, s2, 0
	s_cmp_ge_u32 s73, 16
	s_addc_u32 s2, s2, 0
	s_lshl_b32 s2, s2, 2
	s_and_b32 s36, s92, 7
	s_lshl_b32 s36, s36, 3
	s_lshr_b32 s37, s92, 6
	s_lshl_b32 s37, s37, 1
	s_add_i32 s4, s36, s37
	s_bfe_u32 s37, s92, 0x10003
	s_add_i32 s4, s4, s37
	s_lshr_b32 s37, s92, 5
	s_add_i32 s37, s36, s37
	s_cmp_eq_u32 s73, 16
	s_cselect_b32 s37, s37, s4
	s_mov_b32 s36, s4
	s_lshr_b32 s5, s36, 4
	s_and_b32 s4, s36, 15
	s_lshl_b32 s4, s4, 8
	s_lshl_b32 s36, s5, 6
	s_add_i32 s36, s36, 0x240
	s_cmp_eq_u32 s5, 3
	s_cselect_b32 s36, 0x12c0, s36
	s_add_i32 s36, s36, s4
	s_lshr_b32 s5, s37, 4
	s_and_b32 s4, s37, 15
	s_lshl_b32 s4, s4, 8
	s_lshl_b32 s37, s5, 6
	s_add_i32 s37, s37, 0x240
	s_cmp_eq_u32 s5, 3
	s_cselect_b32 s37, 0x12c0, s37
	s_add_i32 s37, s37, s4
	v_readlane_b32 s4, v253, 3
	v_readlane_b32 s5, v253, 4
	v_mov_b32_e32 v1, s36
	v_mov_b32_e32 v4, s37
	v_mov_b32_e32 v3, 1
	s_nop 2
	global_atomic_add v1, v3, s[4:5]
	buffer_inv sc1
	s_mov_b32 s36, 0
